# MO8+TRIM+IL (SP1: first LDS-DMA load moved up behind the 8th LDS read; SP2: reads interleaved with the loads) + Z0b
# speedup vs baseline: 1.0069x; 1.0017x over previous
.LBB0_139:
	s_add_u32 s22, s18, 0xfff00080
	s_addc_u32 s23, s19, -1
	s_add_i32 s49, 0, 0x10000
	s_cmp_eq_u32 s48, 60
	s_cselect_b32 s25, s9, s23
	s_cselect_b32 s24, s44, s22
	s_cselect_b32 s23, s7, s47
	s_cselect_b32 s22, s45, s46
	s_add_i32 s52, 0, 0x14000
	v_add_u32_e32 v156, s49, v145
	v_add_u32_e32 v172, s52, v145
	ds_read_b128 v[140:143], v156
	ds_read_b128 v[148:151], v156 offset:1024
	ds_read_b128 v[152:155], v156 offset:2048
	ds_read_b128 v[156:159], v156 offset:3072
	ds_read_b128 v[160:163], v172
	ds_read_b128 v[164:167], v172 offset:1024
	ds_read_b128 v[168:171], v172 offset:2048
	ds_read_b128 v[190:193], v172 offset:3072
	v_lshl_add_u64 v[172:173], s[18:19], 0, v[136:137]
	s_add_i32 m0, s31, 0xc000
	s_nop 0
	global_load_lds_dwordx4 v[172:173], off
	ds_read_b128 v[194:197], v147
	ds_read_b128 v[198:201], v147 offset:1024
	ds_read_b128 v[202:205], v147 offset:2048
	ds_read_b128 v[206:209], v147 offset:3072
	ds_read_b128 v[228:231], v147 offset:4096
	ds_read_b128 v[232:235], v147 offset:5120
	ds_read_b128 v[236:239], v147 offset:6144
	ds_read_b128 v[240:243], v147 offset:7168
	v_lshl_add_u64 v[172:173], s[18:19], 0, v[138:139]
	s_add_i32 m0, s31, 0xe000
	s_nop 0
	global_load_lds_dwordx4 v[172:173], off
	s_cmp_eq_u32 s48, -2
	s_cbranch_scc1 .Lz0_0_0
	s_waitcnt vmcnt(8)
	s_waitcnt lgkmcnt(0)
	s_setprio 1
	s_barrier
	v_mfma_f32_16x16x32_bf16 v[126:129], v[140:143], v[194:197], v[126:129]
	v_mfma_f32_16x16x32_bf16 v[126:129], v[148:151], v[198:201], v[126:129]
	v_mfma_f32_16x16x32_bf16 v[118:121], v[148:151], v[206:209], v[118:121]
	v_mfma_f32_16x16x32_bf16 v[118:121], v[140:143], v[202:205], v[118:121]
	v_mfma_f32_16x16x32_bf16 v[102:105], v[140:143], v[228:231], v[102:105]
	v_mfma_f32_16x16x32_bf16 v[102:105], v[148:151], v[232:235], v[102:105]
	v_mfma_f32_16x16x32_bf16 v[86:89], v[148:151], v[240:243], v[86:89]
	v_mfma_f32_16x16x32_bf16 v[86:89], v[140:143], v[236:239], v[86:89]
	v_mfma_f32_16x16x32_bf16 v[78:81], v[152:155], v[236:239], v[78:81]
	v_mfma_f32_16x16x32_bf16 v[78:81], v[156:159], v[240:243], v[78:81]
	v_mfma_f32_16x16x32_bf16 v[94:97], v[156:159], v[232:235], v[94:97]
	v_mfma_f32_16x16x32_bf16 v[94:97], v[152:155], v[228:231], v[94:97]
	v_mfma_f32_16x16x32_bf16 v[110:113], v[152:155], v[202:205], v[110:113]
	v_mfma_f32_16x16x32_bf16 v[110:113], v[156:159], v[206:209], v[110:113]
	v_mfma_f32_16x16x32_bf16 v[122:125], v[156:159], v[198:201], v[122:125]
	v_mfma_f32_16x16x32_bf16 v[122:125], v[152:155], v[194:197], v[122:125]
	v_mfma_f32_16x16x32_bf16 v[114:117], v[160:163], v[194:197], v[114:117]
	v_mfma_f32_16x16x32_bf16 v[114:117], v[164:167], v[198:201], v[114:117]
	v_mfma_f32_16x16x32_bf16 v[98:101], v[164:167], v[206:209], v[98:101]
	v_mfma_f32_16x16x32_bf16 v[98:101], v[160:163], v[202:205], v[98:101]
	v_mfma_f32_16x16x32_bf16 v[82:85], v[160:163], v[228:231], v[82:85]
	v_mfma_f32_16x16x32_bf16 v[82:85], v[164:167], v[232:235], v[82:85]
	v_mfma_f32_16x16x32_bf16 v[70:73], v[164:167], v[240:243], v[70:73]
	v_mfma_f32_16x16x32_bf16 v[70:73], v[160:163], v[236:239], v[70:73]
	v_mfma_f32_16x16x32_bf16 v[66:69], v[168:171], v[236:239], v[66:69]
	v_mfma_f32_16x16x32_bf16 v[66:69], v[190:193], v[240:243], v[66:69]
	v_mfma_f32_16x16x32_bf16 v[74:77], v[190:193], v[232:235], v[74:77]
	v_mfma_f32_16x16x32_bf16 v[74:77], v[168:171], v[228:231], v[74:77]
	v_mfma_f32_16x16x32_bf16 v[90:93], v[168:171], v[202:205], v[90:93]
	v_mfma_f32_16x16x32_bf16 v[90:93], v[190:193], v[206:209], v[90:93]
	v_mfma_f32_16x16x32_bf16 v[106:109], v[190:193], v[198:201], v[106:109]
	v_mfma_f32_16x16x32_bf16 v[106:109], v[168:171], v[194:197], v[106:109]
	s_barrier
	s_setprio 0

.Lz0_0_1_ret:
	s_add_i32 s49, 0, 0x18000
	s_add_i32 s50, 0, 0x1c000
	s_add_u32 s24, s24, 0x100000
	s_addc_u32 s25, s25, 0
	v_add_u32_e32 v156, s49, v145
	v_add_u32_e32 v175, s50, v145
	ds_read_b128 v[140:143], v156
	ds_read_b128 v[148:151], v156 offset:1024
	ds_read_b128 v[152:155], v156 offset:2048
	ds_read_b128 v[156:159], v156 offset:3072
	ds_read_b128 v[160:163], v175
	ds_read_b128 v[164:167], v175 offset:1024
	ds_read_b128 v[168:171], v175 offset:2048
	ds_read_b128 v[190:193], v175 offset:3072
	s_mov_b32 m0, s37
	v_lshl_add_u64 v[244:245], s[24:25], 0, v[134:135]
	global_load_lds_dwordx4 v[244:245], off
	ds_read_b128 v[194:197], v147 offset:32768
	ds_read_b128 v[198:201], v147 offset:33792
	ds_read_b128 v[202:205], v147 offset:34816
	ds_read_b128 v[206:209], v147 offset:35840
	ds_read_b128 v[228:231], v147 offset:36864
	ds_read_b128 v[232:235], v147 offset:37888
	ds_read_b128 v[236:239], v147 offset:38912
	ds_read_b128 v[240:243], v147 offset:39936
	v_lshl_add_u64 v[244:245], s[24:25], 0, v[132:133]
	s_mov_b32 m0, s38
	s_nop 0
	global_load_lds_dwordx4 v[244:245], off
	s_waitcnt vmcnt(8)
	s_waitcnt lgkmcnt(0)
	s_setprio 1
	s_barrier
	v_mfma_f32_16x16x32_bf16 v[126:129], v[140:143], v[194:197], v[126:129]
	v_mfma_f32_16x16x32_bf16 v[126:129], v[148:151], v[198:201], v[126:129]
	v_mfma_f32_16x16x32_bf16 v[118:121], v[148:151], v[206:209], v[118:121]
	v_mfma_f32_16x16x32_bf16 v[118:121], v[140:143], v[202:205], v[118:121]
	v_mfma_f32_16x16x32_bf16 v[102:105], v[140:143], v[228:231], v[102:105]
	v_mfma_f32_16x16x32_bf16 v[102:105], v[148:151], v[232:235], v[102:105]
	v_mfma_f32_16x16x32_bf16 v[86:89], v[148:151], v[240:243], v[86:89]
	v_mfma_f32_16x16x32_bf16 v[86:89], v[140:143], v[236:239], v[86:89]
	v_mfma_f32_16x16x32_bf16 v[78:81], v[152:155], v[236:239], v[78:81]
	v_mfma_f32_16x16x32_bf16 v[78:81], v[156:159], v[240:243], v[78:81]
	v_mfma_f32_16x16x32_bf16 v[94:97], v[156:159], v[232:235], v[94:97]
	v_mfma_f32_16x16x32_bf16 v[94:97], v[152:155], v[228:231], v[94:97]
	v_mfma_f32_16x16x32_bf16 v[110:113], v[152:155], v[202:205], v[110:113]
	v_mfma_f32_16x16x32_bf16 v[110:113], v[156:159], v[206:209], v[110:113]
	v_mfma_f32_16x16x32_bf16 v[122:125], v[156:159], v[198:201], v[122:125]
	v_mfma_f32_16x16x32_bf16 v[122:125], v[152:155], v[194:197], v[122:125]
	v_mfma_f32_16x16x32_bf16 v[114:117], v[160:163], v[194:197], v[114:117]
	v_mfma_f32_16x16x32_bf16 v[114:117], v[164:167], v[198:201], v[114:117]
	v_mfma_f32_16x16x32_bf16 v[98:101], v[164:167], v[206:209], v[98:101]
	v_mfma_f32_16x16x32_bf16 v[98:101], v[160:163], v[202:205], v[98:101]
	v_mfma_f32_16x16x32_bf16 v[82:85], v[160:163], v[228:231], v[82:85]
	v_mfma_f32_16x16x32_bf16 v[82:85], v[164:167], v[232:235], v[82:85]
	v_mfma_f32_16x16x32_bf16 v[70:73], v[164:167], v[240:243], v[70:73]
	v_mfma_f32_16x16x32_bf16 v[70:73], v[160:163], v[236:239], v[70:73]
	v_mfma_f32_16x16x32_bf16 v[66:69], v[168:171], v[236:239], v[66:69]
	v_mfma_f32_16x16x32_bf16 v[66:69], v[190:193], v[240:243], v[66:69]
	v_mfma_f32_16x16x32_bf16 v[74:77], v[190:193], v[232:235], v[74:77]
	v_mfma_f32_16x16x32_bf16 v[74:77], v[168:171], v[228:231], v[74:77]
	v_mfma_f32_16x16x32_bf16 v[90:93], v[168:171], v[202:205], v[90:93]
	v_mfma_f32_16x16x32_bf16 v[90:93], v[190:193], v[206:209], v[90:93]
	v_mfma_f32_16x16x32_bf16 v[106:109], v[190:193], v[198:201], v[106:109]
	v_mfma_f32_16x16x32_bf16 v[106:109], v[168:171], v[194:197], v[106:109]
	s_barrier
	s_setprio 0
	s_add_i32 s24, s49, s26
	v_lshl_add_u64 v[172:173], v[172:173], 0, s[34:35]
	s_mov_b32 m0, s24
	s_nop 0
	global_load_lds_dwordx4 v[172:173], off
	ds_read_b128 v[194:197], v147 offset:49152
	ds_read_b128 v[198:201], v147 offset:50176
	s_add_i32 m0, s24, 0x2000
	s_add_u32 s22, s22, 0x100080
	v_lshl_add_u64 v[172:173], v[178:179], 0, s[34:35]
	s_addc_u32 s23, s23, 0
	s_add_i32 s24, s50, s26
	global_load_lds_dwordx4 v[172:173], off
	ds_read_b128 v[202:205], v147 offset:51200
	ds_read_b128 v[206:209], v147 offset:52224
	v_lshl_add_u64 v[172:173], s[22:23], 0, v[0:1]
	s_mov_b32 m0, s24
	s_nop 0
	global_load_lds_dwordx4 v[172:173], off
	ds_read_b128 v[228:231], v147 offset:53248
	ds_read_b128 v[232:235], v147 offset:54272
	v_lshl_add_u64 v[172:173], s[22:23], 0, v[130:131]
	s_add_i32 m0, s24, 0x2000
	s_nop 0
	global_load_lds_dwordx4 v[172:173], off
	ds_read_b128 v[236:239], v147 offset:55296
	ds_read_b128 v[240:243], v147 offset:56320
	v_lshl_add_u64 v[172:173], v[180:181], 0, s[34:35]
	s_mov_b32 m0, s39
	s_nop 0
	global_load_lds_dwordx4 v[172:173], off
	v_lshl_add_u64 v[172:173], v[210:211], 0, s[34:35]
	s_mov_b32 m0, s40
	s_nop 0
	global_load_lds_dwordx4 v[172:173], off
	s_waitcnt vmcnt(8)
	s_waitcnt lgkmcnt(0)
	s_setprio 1
	s_barrier
	v_mfma_f32_16x16x32_bf16 v[62:65], v[140:143], v[194:197], v[62:65]
	v_mfma_f32_16x16x32_bf16 v[62:65], v[148:151], v[198:201], v[62:65]
	v_mfma_f32_16x16x32_bf16 v[54:57], v[148:151], v[206:209], v[54:57]
	v_mfma_f32_16x16x32_bf16 v[54:57], v[140:143], v[202:205], v[54:57]
	v_mfma_f32_16x16x32_bf16 v[38:41], v[140:143], v[228:231], v[38:41]
	v_mfma_f32_16x16x32_bf16 v[38:41], v[148:151], v[232:235], v[38:41]
	v_mfma_f32_16x16x32_bf16 v[22:25], v[148:151], v[240:243], v[22:25]
	v_mfma_f32_16x16x32_bf16 v[22:25], v[140:143], v[236:239], v[22:25]
	v_mfma_f32_16x16x32_bf16 v[14:17], v[152:155], v[236:239], v[14:17]
	v_mfma_f32_16x16x32_bf16 v[14:17], v[156:159], v[240:243], v[14:17]
	v_mfma_f32_16x16x32_bf16 v[30:33], v[156:159], v[232:235], v[30:33]
	v_mfma_f32_16x16x32_bf16 v[30:33], v[152:155], v[228:231], v[30:33]
	v_mfma_f32_16x16x32_bf16 v[46:49], v[152:155], v[202:205], v[46:49]
	v_mfma_f32_16x16x32_bf16 v[46:49], v[156:159], v[206:209], v[46:49]
	v_mfma_f32_16x16x32_bf16 v[58:61], v[156:159], v[198:201], v[58:61]
	v_mfma_f32_16x16x32_bf16 v[58:61], v[152:155], v[194:197], v[58:61]
	v_mfma_f32_16x16x32_bf16 v[50:53], v[160:163], v[194:197], v[50:53]
	v_mfma_f32_16x16x32_bf16 v[50:53], v[164:167], v[198:201], v[50:53]
	v_mfma_f32_16x16x32_bf16 v[34:37], v[164:167], v[206:209], v[34:37]
	v_mfma_f32_16x16x32_bf16 v[34:37], v[160:163], v[202:205], v[34:37]
	v_mfma_f32_16x16x32_bf16 v[18:21], v[160:163], v[228:231], v[18:21]
	v_mfma_f32_16x16x32_bf16 v[18:21], v[164:167], v[232:235], v[18:21]
	v_mfma_f32_16x16x32_bf16 v[6:9], v[164:167], v[240:243], v[6:9]
	v_mfma_f32_16x16x32_bf16 v[6:9], v[160:163], v[236:239], v[6:9]
	v_mfma_f32_16x16x32_bf16 v[2:5], v[168:171], v[236:239], v[2:5]
	v_mfma_f32_16x16x32_bf16 v[2:5], v[190:193], v[240:243], v[2:5]
	v_mfma_f32_16x16x32_bf16 v[10:13], v[190:193], v[232:235], v[10:13]
	v_mfma_f32_16x16x32_bf16 v[10:13], v[168:171], v[228:231], v[10:13]
	v_mfma_f32_16x16x32_bf16 v[26:29], v[168:171], v[202:205], v[26:29]
	v_mfma_f32_16x16x32_bf16 v[26:29], v[190:193], v[206:209], v[26:29]
	v_mfma_f32_16x16x32_bf16 v[42:45], v[190:193], v[198:201], v[42:45]
	v_mfma_f32_16x16x32_bf16 v[42:45], v[168:171], v[194:197], v[42:45]
	s_barrier
	s_setprio 0
	s_add_i32 s48, s48, 2
	s_add_u32 s18, s18, 0x100
	s_addc_u32 s19, s19, 0
	s_add_u32 s46, s46, 0x100
	s_addc_u32 s47, s47, 0
	s_cmp_gt_u32 s48, 61
	s_cbranch_scc0 .LBB0_139
	s_and_b64 vcc, exec, s[4:5]
	s_cbranch_vccz .LBB0_142
	s_barrier

.LBB0_575:
	s_add_u32 s22, s18, 0xfff00080
	s_addc_u32 s23, s19, -1
	s_add_i32 s53, 0, 0x10000
	s_cmp_eq_u32 s52, 60
	s_cselect_b32 s25, s9, s23
	s_cselect_b32 s24, s48, s22
	s_cselect_b32 s23, s7, s51
	s_cselect_b32 s22, s49, s50
	s_add_i32 s56, 0, 0x14000
	v_add_u32_e32 v140, s53, v143
	ds_read_b128 v[146:149], v140
	ds_read_b128 v[150:153], v140 offset:1024
	ds_read_b128 v[154:157], v140 offset:2048
	ds_read_b128 v[158:161], v140 offset:3072
	v_add_u32_e32 v140, s56, v143
	ds_read_b128 v[162:165], v140
	ds_read_b128 v[166:169], v140 offset:1024
	ds_read_b128 v[170:173], v140 offset:2048
	ds_read_b128 v[178:181], v140 offset:3072
	v_lshl_add_u64 v[140:141], s[18:19], 0, v[136:137]
	s_add_i32 m0, s39, 0xc000
	s_nop 0
	global_load_lds_dwordx4 v[140:141], off
	ds_read_b128 v[190:193], v145
	ds_read_b128 v[194:197], v145 offset:1024
	ds_read_b128 v[198:201], v145 offset:2048
	ds_read_b128 v[202:205], v145 offset:3072
	ds_read_b128 v[206:209], v145 offset:4096
	ds_read_b128 v[228:231], v145 offset:5120
	ds_read_b128 v[232:235], v145 offset:6144
	ds_read_b128 v[236:239], v145 offset:7168
	v_lshl_add_u64 v[140:141], s[18:19], 0, v[138:139]
	s_add_i32 m0, s39, 0xe000
	s_nop 0
	global_load_lds_dwordx4 v[140:141], off
	s_cmp_eq_u32 s52, -2
	s_cbranch_scc1 .Lz0_1_0
	s_waitcnt vmcnt(8)
	s_waitcnt lgkmcnt(0)
	s_setprio 1
	s_barrier
	v_mfma_f32_16x16x32_bf16 v[126:129], v[146:149], v[190:193], v[126:129]
	v_mfma_f32_16x16x32_bf16 v[126:129], v[150:153], v[194:197], v[126:129]
	v_mfma_f32_16x16x32_bf16 v[118:121], v[150:153], v[202:205], v[118:121]
	v_mfma_f32_16x16x32_bf16 v[118:121], v[146:149], v[198:201], v[118:121]
	v_mfma_f32_16x16x32_bf16 v[102:105], v[146:149], v[206:209], v[102:105]
	v_mfma_f32_16x16x32_bf16 v[102:105], v[150:153], v[228:231], v[102:105]
	v_mfma_f32_16x16x32_bf16 v[86:89], v[150:153], v[236:239], v[86:89]
	v_mfma_f32_16x16x32_bf16 v[86:89], v[146:149], v[232:235], v[86:89]
	v_mfma_f32_16x16x32_bf16 v[78:81], v[154:157], v[232:235], v[78:81]
	v_mfma_f32_16x16x32_bf16 v[78:81], v[158:161], v[236:239], v[78:81]
	v_mfma_f32_16x16x32_bf16 v[94:97], v[158:161], v[228:231], v[94:97]
	v_mfma_f32_16x16x32_bf16 v[94:97], v[154:157], v[206:209], v[94:97]
	v_mfma_f32_16x16x32_bf16 v[110:113], v[154:157], v[198:201], v[110:113]
	v_mfma_f32_16x16x32_bf16 v[110:113], v[158:161], v[202:205], v[110:113]
	v_mfma_f32_16x16x32_bf16 v[122:125], v[158:161], v[194:197], v[122:125]
	v_mfma_f32_16x16x32_bf16 v[122:125], v[154:157], v[190:193], v[122:125]
	v_mfma_f32_16x16x32_bf16 v[114:117], v[162:165], v[190:193], v[114:117]
	v_mfma_f32_16x16x32_bf16 v[114:117], v[166:169], v[194:197], v[114:117]
	v_mfma_f32_16x16x32_bf16 v[98:101], v[166:169], v[202:205], v[98:101]
	v_mfma_f32_16x16x32_bf16 v[98:101], v[162:165], v[198:201], v[98:101]
	v_mfma_f32_16x16x32_bf16 v[82:85], v[162:165], v[206:209], v[82:85]
	v_mfma_f32_16x16x32_bf16 v[82:85], v[166:169], v[228:231], v[82:85]
	v_mfma_f32_16x16x32_bf16 v[70:73], v[166:169], v[236:239], v[70:73]
	v_mfma_f32_16x16x32_bf16 v[70:73], v[162:165], v[232:235], v[70:73]
	v_mfma_f32_16x16x32_bf16 v[66:69], v[170:173], v[232:235], v[66:69]
	v_mfma_f32_16x16x32_bf16 v[66:69], v[178:181], v[236:239], v[66:69]
	v_mfma_f32_16x16x32_bf16 v[74:77], v[178:181], v[228:231], v[74:77]
	v_mfma_f32_16x16x32_bf16 v[74:77], v[170:173], v[206:209], v[74:77]
	v_mfma_f32_16x16x32_bf16 v[90:93], v[170:173], v[198:201], v[90:93]
	v_mfma_f32_16x16x32_bf16 v[90:93], v[178:181], v[202:205], v[90:93]
	v_mfma_f32_16x16x32_bf16 v[106:109], v[178:181], v[194:197], v[106:109]
	v_mfma_f32_16x16x32_bf16 v[106:109], v[170:173], v[190:193], v[106:109]
	s_barrier
	s_setprio 0

.Lz0_1_1_ret:
	s_add_i32 s53, 0, 0x18000
	s_add_i32 s54, 0, 0x1c000
	s_add_u32 s24, s24, 0x100000
	s_addc_u32 s25, s25, 0
	v_add_u32_e32 v158, s53, v143
	v_add_u32_e32 v175, s54, v143
	ds_read_b128 v[146:149], v158
	ds_read_b128 v[150:153], v158 offset:1024
	ds_read_b128 v[154:157], v158 offset:2048
	ds_read_b128 v[158:161], v158 offset:3072
	ds_read_b128 v[162:165], v175
	ds_read_b128 v[166:169], v175 offset:1024
	ds_read_b128 v[170:173], v175 offset:2048
	ds_read_b128 v[178:181], v175 offset:3072
	s_mov_b32 m0, s41
	v_lshl_add_u64 v[226:227], s[24:25], 0, v[134:135]
	global_load_lds_dwordx4 v[226:227], off
	ds_read_b128 v[190:193], v145 offset:32768
	ds_read_b128 v[194:197], v145 offset:33792
	ds_read_b128 v[198:201], v145 offset:34816
	ds_read_b128 v[202:205], v145 offset:35840
	ds_read_b128 v[206:209], v145 offset:36864
	ds_read_b128 v[228:231], v145 offset:37888
	ds_read_b128 v[232:235], v145 offset:38912
	ds_read_b128 v[236:239], v145 offset:39936
	v_lshl_add_u64 v[226:227], s[24:25], 0, v[132:133]
	s_mov_b32 m0, s42
	s_nop 0
	global_load_lds_dwordx4 v[226:227], off
	s_waitcnt vmcnt(8)
	s_waitcnt lgkmcnt(0)
	s_setprio 1
	s_barrier
	v_mfma_f32_16x16x32_bf16 v[126:129], v[146:149], v[190:193], v[126:129]
	v_mfma_f32_16x16x32_bf16 v[126:129], v[150:153], v[194:197], v[126:129]
	v_mfma_f32_16x16x32_bf16 v[118:121], v[150:153], v[202:205], v[118:121]
	v_mfma_f32_16x16x32_bf16 v[118:121], v[146:149], v[198:201], v[118:121]
	v_mfma_f32_16x16x32_bf16 v[102:105], v[146:149], v[206:209], v[102:105]
	v_mfma_f32_16x16x32_bf16 v[102:105], v[150:153], v[228:231], v[102:105]
	v_mfma_f32_16x16x32_bf16 v[86:89], v[150:153], v[236:239], v[86:89]
	v_mfma_f32_16x16x32_bf16 v[86:89], v[146:149], v[232:235], v[86:89]
	v_mfma_f32_16x16x32_bf16 v[78:81], v[154:157], v[232:235], v[78:81]
	v_mfma_f32_16x16x32_bf16 v[78:81], v[158:161], v[236:239], v[78:81]
	v_mfma_f32_16x16x32_bf16 v[94:97], v[158:161], v[228:231], v[94:97]
	v_mfma_f32_16x16x32_bf16 v[94:97], v[154:157], v[206:209], v[94:97]
	v_mfma_f32_16x16x32_bf16 v[110:113], v[154:157], v[198:201], v[110:113]
	v_mfma_f32_16x16x32_bf16 v[110:113], v[158:161], v[202:205], v[110:113]
	v_mfma_f32_16x16x32_bf16 v[122:125], v[158:161], v[194:197], v[122:125]
	v_mfma_f32_16x16x32_bf16 v[122:125], v[154:157], v[190:193], v[122:125]
	v_mfma_f32_16x16x32_bf16 v[114:117], v[162:165], v[190:193], v[114:117]
	v_mfma_f32_16x16x32_bf16 v[114:117], v[166:169], v[194:197], v[114:117]
	v_mfma_f32_16x16x32_bf16 v[98:101], v[166:169], v[202:205], v[98:101]
	v_mfma_f32_16x16x32_bf16 v[98:101], v[162:165], v[198:201], v[98:101]
	v_mfma_f32_16x16x32_bf16 v[82:85], v[162:165], v[206:209], v[82:85]
	v_mfma_f32_16x16x32_bf16 v[82:85], v[166:169], v[228:231], v[82:85]
	v_mfma_f32_16x16x32_bf16 v[70:73], v[166:169], v[236:239], v[70:73]
	v_mfma_f32_16x16x32_bf16 v[70:73], v[162:165], v[232:235], v[70:73]
	v_mfma_f32_16x16x32_bf16 v[66:69], v[170:173], v[232:235], v[66:69]
	v_mfma_f32_16x16x32_bf16 v[66:69], v[178:181], v[236:239], v[66:69]
	v_mfma_f32_16x16x32_bf16 v[74:77], v[178:181], v[228:231], v[74:77]
	v_mfma_f32_16x16x32_bf16 v[74:77], v[170:173], v[206:209], v[74:77]
	v_mfma_f32_16x16x32_bf16 v[90:93], v[170:173], v[198:201], v[90:93]
	v_mfma_f32_16x16x32_bf16 v[90:93], v[178:181], v[202:205], v[90:93]
	v_mfma_f32_16x16x32_bf16 v[106:109], v[178:181], v[194:197], v[106:109]
	v_mfma_f32_16x16x32_bf16 v[106:109], v[170:173], v[190:193], v[106:109]
	s_barrier
	s_setprio 0
	s_add_i32 s24, s53, s38
	v_lshl_add_u64 v[140:141], v[140:141], 0, s[34:35]
	s_mov_b32 m0, s24
	s_nop 0
	global_load_lds_dwordx4 v[140:141], off
	ds_read_b128 v[190:193], v145 offset:49152
	ds_read_b128 v[194:197], v145 offset:50176
	s_add_i32 m0, s24, 0x2000
	s_add_u32 s22, s22, 0x100080
	v_lshl_add_u64 v[140:141], v[186:187], 0, s[34:35]
	s_addc_u32 s23, s23, 0
	s_add_i32 s24, s54, s38
	global_load_lds_dwordx4 v[140:141], off
	ds_read_b128 v[198:201], v145 offset:51200
	ds_read_b128 v[202:205], v145 offset:52224
	v_lshl_add_u64 v[140:141], s[22:23], 0, v[0:1]
	s_mov_b32 m0, s24
	s_nop 0
	global_load_lds_dwordx4 v[140:141], off
	ds_read_b128 v[206:209], v145 offset:53248
	ds_read_b128 v[228:231], v145 offset:54272
	v_lshl_add_u64 v[140:141], s[22:23], 0, v[130:131]
	s_add_i32 m0, s24, 0x2000
	s_nop 0
	global_load_lds_dwordx4 v[140:141], off
	ds_read_b128 v[232:235], v145 offset:55296
	ds_read_b128 v[236:239], v145 offset:56320
	v_lshl_add_u64 v[140:141], v[188:189], 0, s[34:35]
	s_mov_b32 m0, s43
	s_nop 0
	global_load_lds_dwordx4 v[140:141], off
	v_lshl_add_u64 v[140:141], v[210:211], 0, s[34:35]
	s_mov_b32 m0, s44
	s_nop 0
	global_load_lds_dwordx4 v[140:141], off
	s_waitcnt vmcnt(8)
	s_waitcnt lgkmcnt(0)
	s_setprio 1
	s_barrier
	v_mfma_f32_16x16x32_bf16 v[62:65], v[146:149], v[190:193], v[62:65]
	v_mfma_f32_16x16x32_bf16 v[62:65], v[150:153], v[194:197], v[62:65]
	v_mfma_f32_16x16x32_bf16 v[54:57], v[150:153], v[202:205], v[54:57]
	v_mfma_f32_16x16x32_bf16 v[54:57], v[146:149], v[198:201], v[54:57]
	v_mfma_f32_16x16x32_bf16 v[38:41], v[146:149], v[206:209], v[38:41]
	v_mfma_f32_16x16x32_bf16 v[38:41], v[150:153], v[228:231], v[38:41]
	v_mfma_f32_16x16x32_bf16 v[22:25], v[150:153], v[236:239], v[22:25]
	v_mfma_f32_16x16x32_bf16 v[22:25], v[146:149], v[232:235], v[22:25]
	v_mfma_f32_16x16x32_bf16 v[14:17], v[154:157], v[232:235], v[14:17]
	v_mfma_f32_16x16x32_bf16 v[14:17], v[158:161], v[236:239], v[14:17]
	v_mfma_f32_16x16x32_bf16 v[30:33], v[158:161], v[228:231], v[30:33]
	v_mfma_f32_16x16x32_bf16 v[30:33], v[154:157], v[206:209], v[30:33]
	v_mfma_f32_16x16x32_bf16 v[46:49], v[154:157], v[198:201], v[46:49]
	v_mfma_f32_16x16x32_bf16 v[46:49], v[158:161], v[202:205], v[46:49]
	v_mfma_f32_16x16x32_bf16 v[58:61], v[158:161], v[194:197], v[58:61]
	v_mfma_f32_16x16x32_bf16 v[58:61], v[154:157], v[190:193], v[58:61]
	v_mfma_f32_16x16x32_bf16 v[50:53], v[162:165], v[190:193], v[50:53]
	v_mfma_f32_16x16x32_bf16 v[50:53], v[166:169], v[194:197], v[50:53]
	v_mfma_f32_16x16x32_bf16 v[34:37], v[166:169], v[202:205], v[34:37]
	v_mfma_f32_16x16x32_bf16 v[34:37], v[162:165], v[198:201], v[34:37]
	v_mfma_f32_16x16x32_bf16 v[18:21], v[162:165], v[206:209], v[18:21]
	v_mfma_f32_16x16x32_bf16 v[18:21], v[166:169], v[228:231], v[18:21]
	v_mfma_f32_16x16x32_bf16 v[6:9], v[166:169], v[236:239], v[6:9]
	v_mfma_f32_16x16x32_bf16 v[6:9], v[162:165], v[232:235], v[6:9]
	v_mfma_f32_16x16x32_bf16 v[2:5], v[170:173], v[232:235], v[2:5]
	v_mfma_f32_16x16x32_bf16 v[2:5], v[178:181], v[236:239], v[2:5]
	v_mfma_f32_16x16x32_bf16 v[10:13], v[178:181], v[228:231], v[10:13]
	v_mfma_f32_16x16x32_bf16 v[10:13], v[170:173], v[206:209], v[10:13]
	v_mfma_f32_16x16x32_bf16 v[26:29], v[170:173], v[198:201], v[26:29]
	v_mfma_f32_16x16x32_bf16 v[26:29], v[178:181], v[202:205], v[26:29]
	v_mfma_f32_16x16x32_bf16 v[42:45], v[178:181], v[194:197], v[42:45]
	v_mfma_f32_16x16x32_bf16 v[42:45], v[170:173], v[190:193], v[42:45]
	s_barrier
	s_setprio 0
	s_add_i32 s52, s52, 2
	s_add_u32 s18, s18, 0x100
	s_addc_u32 s19, s19, 0
	s_add_u32 s50, s50, 0x100
	s_addc_u32 s51, s51, 0
	s_cmp_gt_u32 s52, 61
	s_cbranch_scc0 .LBB0_575
	s_and_b64 vcc, exec, s[4:5]
	s_cbranch_vccz .LBB0_578
	s_barrier

.LBB0_721:
	s_add_u32 s18, s16, 0xfff00080
	s_addc_u32 s19, s17, -1
	s_add_i32 s53, 0, 0x10000
	s_cmp_eq_u32 s52, 60
	s_cselect_b32 s23, s7, s19
	s_cselect_b32 s22, s48, s18
	s_cselect_b32 s19, s5, s51
	s_cselect_b32 s18, s49, s50
	s_add_i32 s56, 0, 0x14000
	v_add_u32_e32 v140, s53, v143
	ds_read_b128 v[146:149], v140
	ds_read_b128 v[150:153], v140 offset:1024
	ds_read_b128 v[154:157], v140 offset:2048
	ds_read_b128 v[158:161], v140 offset:3072
	v_add_u32_e32 v140, s56, v143
	ds_read_b128 v[162:165], v140
	ds_read_b128 v[166:169], v140 offset:1024
	ds_read_b128 v[170:173], v140 offset:2048
	ds_read_b128 v[178:181], v140 offset:3072
	v_lshl_add_u64 v[140:141], s[16:17], 0, v[136:137]
	s_add_i32 m0, s31, 0xc000
	s_nop 0
	global_load_lds_dwordx4 v[140:141], off
	ds_read_b128 v[190:193], v145
	ds_read_b128 v[194:197], v145 offset:1024
	ds_read_b128 v[198:201], v145 offset:2048
	ds_read_b128 v[202:205], v145 offset:3072
	ds_read_b128 v[206:209], v145 offset:4096
	ds_read_b128 v[228:231], v145 offset:5120
	ds_read_b128 v[232:235], v145 offset:6144
	ds_read_b128 v[236:239], v145 offset:7168
	v_lshl_add_u64 v[140:141], s[16:17], 0, v[138:139]
	s_add_i32 m0, s31, 0xe000
	s_nop 0
	global_load_lds_dwordx4 v[140:141], off
	s_cmp_eq_u32 s52, -2
	s_cbranch_scc1 .Lz0_2_0
	s_waitcnt vmcnt(8)
	s_waitcnt lgkmcnt(0)
	s_setprio 1
	s_barrier
	v_mfma_f32_16x16x32_bf16 v[126:129], v[146:149], v[190:193], v[126:129]
	v_mfma_f32_16x16x32_bf16 v[126:129], v[150:153], v[194:197], v[126:129]
	v_mfma_f32_16x16x32_bf16 v[110:113], v[150:153], v[202:205], v[110:113]
	v_mfma_f32_16x16x32_bf16 v[110:113], v[146:149], v[198:201], v[110:113]
	v_mfma_f32_16x16x32_bf16 v[94:97], v[146:149], v[206:209], v[94:97]
	v_mfma_f32_16x16x32_bf16 v[94:97], v[150:153], v[228:231], v[94:97]
	v_mfma_f32_16x16x32_bf16 v[78:81], v[150:153], v[236:239], v[78:81]
	v_mfma_f32_16x16x32_bf16 v[78:81], v[146:149], v[232:235], v[78:81]
	v_mfma_f32_16x16x32_bf16 v[70:73], v[154:157], v[232:235], v[70:73]
	v_mfma_f32_16x16x32_bf16 v[70:73], v[158:161], v[236:239], v[70:73]
	v_mfma_f32_16x16x32_bf16 v[86:89], v[158:161], v[228:231], v[86:89]
	v_mfma_f32_16x16x32_bf16 v[86:89], v[154:157], v[206:209], v[86:89]
	v_mfma_f32_16x16x32_bf16 v[102:105], v[154:157], v[198:201], v[102:105]
	v_mfma_f32_16x16x32_bf16 v[102:105], v[158:161], v[202:205], v[102:105]
	v_mfma_f32_16x16x32_bf16 v[118:121], v[158:161], v[194:197], v[118:121]
	v_mfma_f32_16x16x32_bf16 v[118:121], v[154:157], v[190:193], v[118:121]
	v_mfma_f32_16x16x32_bf16 v[122:125], v[162:165], v[190:193], v[122:125]
	v_mfma_f32_16x16x32_bf16 v[122:125], v[166:169], v[194:197], v[122:125]
	v_mfma_f32_16x16x32_bf16 v[106:109], v[166:169], v[202:205], v[106:109]
	v_mfma_f32_16x16x32_bf16 v[106:109], v[162:165], v[198:201], v[106:109]
	v_mfma_f32_16x16x32_bf16 v[90:93], v[162:165], v[206:209], v[90:93]
	v_mfma_f32_16x16x32_bf16 v[90:93], v[166:169], v[228:231], v[90:93]
	v_mfma_f32_16x16x32_bf16 v[74:77], v[166:169], v[236:239], v[74:77]
	v_mfma_f32_16x16x32_bf16 v[74:77], v[162:165], v[232:235], v[74:77]
	v_mfma_f32_16x16x32_bf16 v[66:69], v[170:173], v[232:235], v[66:69]
	v_mfma_f32_16x16x32_bf16 v[66:69], v[178:181], v[236:239], v[66:69]
	v_mfma_f32_16x16x32_bf16 v[82:85], v[178:181], v[228:231], v[82:85]
	v_mfma_f32_16x16x32_bf16 v[82:85], v[170:173], v[206:209], v[82:85]
	v_mfma_f32_16x16x32_bf16 v[98:101], v[170:173], v[198:201], v[98:101]
	v_mfma_f32_16x16x32_bf16 v[98:101], v[178:181], v[202:205], v[98:101]
	v_mfma_f32_16x16x32_bf16 v[114:117], v[178:181], v[194:197], v[114:117]
	v_mfma_f32_16x16x32_bf16 v[114:117], v[170:173], v[190:193], v[114:117]
	s_barrier
	s_setprio 0

.Lz0_2_1_ret:
	s_add_i32 s53, 0, 0x18000
	s_add_i32 s54, 0, 0x1c000
	s_add_u32 s22, s22, 0x100000
	s_addc_u32 s23, s23, 0
	v_add_u32_e32 v158, s53, v143
	v_add_u32_e32 v175, s54, v143
	ds_read_b128 v[146:149], v158
	ds_read_b128 v[150:153], v158 offset:1024
	ds_read_b128 v[154:157], v158 offset:2048
	ds_read_b128 v[158:161], v158 offset:3072
	ds_read_b128 v[162:165], v175
	ds_read_b128 v[166:169], v175 offset:1024
	ds_read_b128 v[170:173], v175 offset:2048
	ds_read_b128 v[178:181], v175 offset:3072
	s_mov_b32 m0, s41
	v_lshl_add_u64 v[226:227], s[22:23], 0, v[134:135]
	global_load_lds_dwordx4 v[226:227], off
	ds_read_b128 v[190:193], v145 offset:32768
	ds_read_b128 v[194:197], v145 offset:33792
	ds_read_b128 v[198:201], v145 offset:34816
	ds_read_b128 v[202:205], v145 offset:35840
	ds_read_b128 v[206:209], v145 offset:36864
	ds_read_b128 v[228:231], v145 offset:37888
	ds_read_b128 v[232:235], v145 offset:38912
	ds_read_b128 v[236:239], v145 offset:39936
	v_lshl_add_u64 v[226:227], s[22:23], 0, v[132:133]
	s_mov_b32 m0, s42
	s_nop 0
	global_load_lds_dwordx4 v[226:227], off
	s_waitcnt vmcnt(8)
	s_waitcnt lgkmcnt(0)
	s_setprio 1
	s_barrier
	v_mfma_f32_16x16x32_bf16 v[126:129], v[146:149], v[190:193], v[126:129]
	v_mfma_f32_16x16x32_bf16 v[126:129], v[150:153], v[194:197], v[126:129]
	v_mfma_f32_16x16x32_bf16 v[110:113], v[150:153], v[202:205], v[110:113]
	v_mfma_f32_16x16x32_bf16 v[110:113], v[146:149], v[198:201], v[110:113]
	v_mfma_f32_16x16x32_bf16 v[94:97], v[146:149], v[206:209], v[94:97]
	v_mfma_f32_16x16x32_bf16 v[94:97], v[150:153], v[228:231], v[94:97]
	v_mfma_f32_16x16x32_bf16 v[78:81], v[150:153], v[236:239], v[78:81]
	v_mfma_f32_16x16x32_bf16 v[78:81], v[146:149], v[232:235], v[78:81]
	v_mfma_f32_16x16x32_bf16 v[70:73], v[154:157], v[232:235], v[70:73]
	v_mfma_f32_16x16x32_bf16 v[70:73], v[158:161], v[236:239], v[70:73]
	v_mfma_f32_16x16x32_bf16 v[86:89], v[158:161], v[228:231], v[86:89]
	v_mfma_f32_16x16x32_bf16 v[86:89], v[154:157], v[206:209], v[86:89]
	v_mfma_f32_16x16x32_bf16 v[102:105], v[154:157], v[198:201], v[102:105]
	v_mfma_f32_16x16x32_bf16 v[102:105], v[158:161], v[202:205], v[102:105]
	v_mfma_f32_16x16x32_bf16 v[118:121], v[158:161], v[194:197], v[118:121]
	v_mfma_f32_16x16x32_bf16 v[118:121], v[154:157], v[190:193], v[118:121]
	v_mfma_f32_16x16x32_bf16 v[122:125], v[162:165], v[190:193], v[122:125]
	v_mfma_f32_16x16x32_bf16 v[122:125], v[166:169], v[194:197], v[122:125]
	v_mfma_f32_16x16x32_bf16 v[106:109], v[166:169], v[202:205], v[106:109]
	v_mfma_f32_16x16x32_bf16 v[106:109], v[162:165], v[198:201], v[106:109]
	v_mfma_f32_16x16x32_bf16 v[90:93], v[162:165], v[206:209], v[90:93]
	v_mfma_f32_16x16x32_bf16 v[90:93], v[166:169], v[228:231], v[90:93]
	v_mfma_f32_16x16x32_bf16 v[74:77], v[166:169], v[236:239], v[74:77]
	v_mfma_f32_16x16x32_bf16 v[74:77], v[162:165], v[232:235], v[74:77]
	v_mfma_f32_16x16x32_bf16 v[66:69], v[170:173], v[232:235], v[66:69]
	v_mfma_f32_16x16x32_bf16 v[66:69], v[178:181], v[236:239], v[66:69]
	v_mfma_f32_16x16x32_bf16 v[82:85], v[178:181], v[228:231], v[82:85]
	v_mfma_f32_16x16x32_bf16 v[82:85], v[170:173], v[206:209], v[82:85]
	v_mfma_f32_16x16x32_bf16 v[98:101], v[170:173], v[198:201], v[98:101]
	v_mfma_f32_16x16x32_bf16 v[98:101], v[178:181], v[202:205], v[98:101]
	v_mfma_f32_16x16x32_bf16 v[114:117], v[178:181], v[194:197], v[114:117]
	v_mfma_f32_16x16x32_bf16 v[114:117], v[170:173], v[190:193], v[114:117]
	s_barrier
	s_setprio 0
	s_add_i32 s22, s53, s26
	v_lshl_add_u64 v[140:141], v[140:141], 0, s[34:35]
	s_mov_b32 m0, s22
	s_nop 0
	global_load_lds_dwordx4 v[140:141], off
	ds_read_b128 v[190:193], v145 offset:49152
	ds_read_b128 v[194:197], v145 offset:50176
	s_add_i32 m0, s22, 0x2000
	s_add_u32 s18, s18, 0x100080
	v_lshl_add_u64 v[140:141], v[186:187], 0, s[34:35]
	s_addc_u32 s19, s19, 0
	s_add_i32 s22, s54, s26
	global_load_lds_dwordx4 v[140:141], off
	ds_read_b128 v[198:201], v145 offset:51200
	ds_read_b128 v[202:205], v145 offset:52224
	v_lshl_add_u64 v[140:141], s[18:19], 0, v[0:1]
	s_mov_b32 m0, s22
	s_nop 0
	global_load_lds_dwordx4 v[140:141], off
	ds_read_b128 v[206:209], v145 offset:53248
	ds_read_b128 v[228:231], v145 offset:54272
	v_lshl_add_u64 v[140:141], s[18:19], 0, v[130:131]
	s_add_i32 m0, s22, 0x2000
	s_nop 0
	global_load_lds_dwordx4 v[140:141], off
	ds_read_b128 v[232:235], v145 offset:55296
	ds_read_b128 v[236:239], v145 offset:56320
	v_lshl_add_u64 v[140:141], v[188:189], 0, s[34:35]
	s_mov_b32 m0, s43
	s_nop 0
	global_load_lds_dwordx4 v[140:141], off
	v_lshl_add_u64 v[140:141], v[210:211], 0, s[34:35]
	s_mov_b32 m0, s44
	s_nop 0
	global_load_lds_dwordx4 v[140:141], off
	s_waitcnt vmcnt(8)
	s_waitcnt lgkmcnt(0)
	s_setprio 1
	s_barrier
	v_mfma_f32_16x16x32_bf16 v[62:65], v[146:149], v[190:193], v[62:65]
	v_mfma_f32_16x16x32_bf16 v[62:65], v[150:153], v[194:197], v[62:65]
	v_mfma_f32_16x16x32_bf16 v[46:49], v[150:153], v[202:205], v[46:49]
	v_mfma_f32_16x16x32_bf16 v[46:49], v[146:149], v[198:201], v[46:49]
	v_mfma_f32_16x16x32_bf16 v[30:33], v[146:149], v[206:209], v[30:33]
	v_mfma_f32_16x16x32_bf16 v[30:33], v[150:153], v[228:231], v[30:33]
	v_mfma_f32_16x16x32_bf16 v[14:17], v[150:153], v[236:239], v[14:17]
	v_mfma_f32_16x16x32_bf16 v[14:17], v[146:149], v[232:235], v[14:17]
	v_mfma_f32_16x16x32_bf16 v[6:9], v[154:157], v[232:235], v[6:9]
	v_mfma_f32_16x16x32_bf16 v[6:9], v[158:161], v[236:239], v[6:9]
	v_mfma_f32_16x16x32_bf16 v[22:25], v[158:161], v[228:231], v[22:25]
	v_mfma_f32_16x16x32_bf16 v[22:25], v[154:157], v[206:209], v[22:25]
	v_mfma_f32_16x16x32_bf16 v[38:41], v[154:157], v[198:201], v[38:41]
	v_mfma_f32_16x16x32_bf16 v[38:41], v[158:161], v[202:205], v[38:41]
	v_mfma_f32_16x16x32_bf16 v[54:57], v[158:161], v[194:197], v[54:57]
	v_mfma_f32_16x16x32_bf16 v[54:57], v[154:157], v[190:193], v[54:57]
	v_mfma_f32_16x16x32_bf16 v[58:61], v[162:165], v[190:193], v[58:61]
	v_mfma_f32_16x16x32_bf16 v[58:61], v[166:169], v[194:197], v[58:61]
	v_mfma_f32_16x16x32_bf16 v[42:45], v[166:169], v[202:205], v[42:45]
	v_mfma_f32_16x16x32_bf16 v[42:45], v[162:165], v[198:201], v[42:45]
	v_mfma_f32_16x16x32_bf16 v[26:29], v[162:165], v[206:209], v[26:29]
	v_mfma_f32_16x16x32_bf16 v[26:29], v[166:169], v[228:231], v[26:29]
	v_mfma_f32_16x16x32_bf16 v[10:13], v[166:169], v[236:239], v[10:13]
	v_mfma_f32_16x16x32_bf16 v[10:13], v[162:165], v[232:235], v[10:13]
	v_mfma_f32_16x16x32_bf16 v[2:5], v[170:173], v[232:235], v[2:5]
	v_mfma_f32_16x16x32_bf16 v[2:5], v[178:181], v[236:239], v[2:5]
	v_mfma_f32_16x16x32_bf16 v[18:21], v[178:181], v[228:231], v[18:21]
	v_mfma_f32_16x16x32_bf16 v[18:21], v[170:173], v[206:209], v[18:21]
	v_mfma_f32_16x16x32_bf16 v[34:37], v[170:173], v[198:201], v[34:37]
	v_mfma_f32_16x16x32_bf16 v[34:37], v[178:181], v[202:205], v[34:37]
	v_mfma_f32_16x16x32_bf16 v[50:53], v[178:181], v[194:197], v[50:53]
	v_mfma_f32_16x16x32_bf16 v[50:53], v[170:173], v[190:193], v[50:53]
	s_barrier
	s_setprio 0
	s_add_i32 s52, s52, 2
	s_add_u32 s16, s16, 0x100
	s_addc_u32 s17, s17, 0
	s_add_u32 s50, s50, 0x100
	s_addc_u32 s51, s51, 0
	s_cmp_gt_u32 s52, 61
	s_cbranch_scc0 .LBB0_721
	s_and_b64 vcc, exec, s[2:3]
	s_cbranch_vccz .LBB0_724
	s_barrier

.LBB0_805:
	s_add_u32 s16, s14, 0x100
	s_addc_u32 s17, s15, 0
	s_add_i32 s49, 0, 0x10000
	s_cmpk_eq_i32 s48, 0xa8
	s_cselect_b32 s23, s5, s17
	s_cselect_b32 s22, s4, s16
	s_cselect_b32 s19, s9, s47
	s_cselect_b32 s18, s8, s46
	s_add_i32 s50, 0, 0x14000
	v_add_u32_e32 v140, s49, v143
	ds_read_b128 v[146:149], v140
	ds_read_b128 v[150:153], v140 offset:1024
	ds_read_b128 v[154:157], v140 offset:2048
	ds_read_b128 v[158:161], v140 offset:3072
	v_add_u32_e32 v140, s50, v143
	ds_read_b128 v[162:165], v140
	ds_read_b128 v[166:169], v140 offset:1024
	ds_read_b128 v[170:173], v140 offset:2048
	ds_read_b128 v[178:181], v140 offset:3072
	v_lshl_add_u64 v[140:141], s[14:15], 0, v[136:137]
	s_add_i32 m0, s31, 0xc000
	s_nop 0
	global_load_lds_dwordx4 v[140:141], off
	ds_read_b128 v[190:193], v145
	ds_read_b128 v[194:197], v145 offset:1024
	ds_read_b128 v[198:201], v145 offset:2048
	ds_read_b128 v[202:205], v145 offset:3072
	ds_read_b128 v[206:209], v145 offset:4096
	ds_read_b128 v[228:231], v145 offset:5120
	ds_read_b128 v[232:235], v145 offset:6144
	ds_read_b128 v[236:239], v145 offset:7168
	v_lshl_add_u64 v[140:141], s[14:15], 0, v[138:139]
	s_add_i32 m0, s31, 0xe000
	s_nop 0
	global_load_lds_dwordx4 v[140:141], off
	s_cmp_eq_u32 s48, -2
	s_cbranch_scc1 .Lz0_3_0
	s_waitcnt vmcnt(8)
	s_waitcnt lgkmcnt(0)
	s_setprio 1
	s_barrier
	v_mfma_f32_16x16x32_bf16 v[126:129], v[146:149], v[190:193], v[126:129]
	v_mfma_f32_16x16x32_bf16 v[126:129], v[150:153], v[194:197], v[126:129]
	v_mfma_f32_16x16x32_bf16 v[118:121], v[150:153], v[202:205], v[118:121]
	v_mfma_f32_16x16x32_bf16 v[118:121], v[146:149], v[198:201], v[118:121]
	v_mfma_f32_16x16x32_bf16 v[102:105], v[146:149], v[206:209], v[102:105]
	v_mfma_f32_16x16x32_bf16 v[102:105], v[150:153], v[228:231], v[102:105]
	v_mfma_f32_16x16x32_bf16 v[86:89], v[150:153], v[236:239], v[86:89]
	v_mfma_f32_16x16x32_bf16 v[86:89], v[146:149], v[232:235], v[86:89]
	v_mfma_f32_16x16x32_bf16 v[78:81], v[154:157], v[232:235], v[78:81]
	v_mfma_f32_16x16x32_bf16 v[78:81], v[158:161], v[236:239], v[78:81]
	v_mfma_f32_16x16x32_bf16 v[94:97], v[158:161], v[228:231], v[94:97]
	v_mfma_f32_16x16x32_bf16 v[94:97], v[154:157], v[206:209], v[94:97]
	v_mfma_f32_16x16x32_bf16 v[110:113], v[154:157], v[198:201], v[110:113]
	v_mfma_f32_16x16x32_bf16 v[110:113], v[158:161], v[202:205], v[110:113]
	v_mfma_f32_16x16x32_bf16 v[122:125], v[158:161], v[194:197], v[122:125]
	v_mfma_f32_16x16x32_bf16 v[122:125], v[154:157], v[190:193], v[122:125]
	v_mfma_f32_16x16x32_bf16 v[114:117], v[162:165], v[190:193], v[114:117]
	v_mfma_f32_16x16x32_bf16 v[114:117], v[166:169], v[194:197], v[114:117]
	v_mfma_f32_16x16x32_bf16 v[98:101], v[166:169], v[202:205], v[98:101]
	v_mfma_f32_16x16x32_bf16 v[98:101], v[162:165], v[198:201], v[98:101]
	v_mfma_f32_16x16x32_bf16 v[82:85], v[162:165], v[206:209], v[82:85]
	v_mfma_f32_16x16x32_bf16 v[82:85], v[166:169], v[228:231], v[82:85]
	v_mfma_f32_16x16x32_bf16 v[70:73], v[166:169], v[236:239], v[70:73]
	v_mfma_f32_16x16x32_bf16 v[70:73], v[162:165], v[232:235], v[70:73]
	v_mfma_f32_16x16x32_bf16 v[66:69], v[170:173], v[232:235], v[66:69]
	v_mfma_f32_16x16x32_bf16 v[66:69], v[178:181], v[236:239], v[66:69]
	v_mfma_f32_16x16x32_bf16 v[74:77], v[178:181], v[228:231], v[74:77]
	v_mfma_f32_16x16x32_bf16 v[74:77], v[170:173], v[206:209], v[74:77]
	v_mfma_f32_16x16x32_bf16 v[90:93], v[170:173], v[198:201], v[90:93]
	v_mfma_f32_16x16x32_bf16 v[90:93], v[178:181], v[202:205], v[90:93]
	v_mfma_f32_16x16x32_bf16 v[106:109], v[178:181], v[194:197], v[106:109]
	v_mfma_f32_16x16x32_bf16 v[106:109], v[170:173], v[190:193], v[106:109]
	s_barrier
	s_setprio 0

.Lz0_3_1_ret:
	s_add_i32 s49, 0, 0x18000
	s_add_i32 s50, 0, 0x1c000
	s_add_u32 s14, s22, 0x2b0000
	s_addc_u32 s15, s23, 0
	v_add_u32_e32 v158, s49, v143
	v_add_u32_e32 v175, s50, v143
	ds_read_b128 v[146:149], v158
	ds_read_b128 v[150:153], v158 offset:1024
	ds_read_b128 v[154:157], v158 offset:2048
	ds_read_b128 v[158:161], v158 offset:3072
	ds_read_b128 v[162:165], v175
	ds_read_b128 v[166:169], v175 offset:1024
	ds_read_b128 v[170:173], v175 offset:2048
	ds_read_b128 v[178:181], v175 offset:3072
	s_mov_b32 m0, s37
	v_lshl_add_u64 v[226:227], s[14:15], 0, v[134:135]
	global_load_lds_dwordx4 v[226:227], off
	ds_read_b128 v[190:193], v145 offset:32768
	ds_read_b128 v[194:197], v145 offset:33792
	ds_read_b128 v[198:201], v145 offset:34816
	ds_read_b128 v[202:205], v145 offset:35840
	ds_read_b128 v[206:209], v145 offset:36864
	ds_read_b128 v[228:231], v145 offset:37888
	ds_read_b128 v[232:235], v145 offset:38912
	ds_read_b128 v[236:239], v145 offset:39936
	v_lshl_add_u64 v[226:227], s[14:15], 0, v[132:133]
	s_mov_b32 m0, s38
	s_nop 0
	global_load_lds_dwordx4 v[226:227], off
	s_waitcnt vmcnt(8)
	s_waitcnt lgkmcnt(0)
	s_setprio 1
	s_barrier
	v_mfma_f32_16x16x32_bf16 v[126:129], v[146:149], v[190:193], v[126:129]
	v_mfma_f32_16x16x32_bf16 v[126:129], v[150:153], v[194:197], v[126:129]
	v_mfma_f32_16x16x32_bf16 v[118:121], v[150:153], v[202:205], v[118:121]
	v_mfma_f32_16x16x32_bf16 v[118:121], v[146:149], v[198:201], v[118:121]
	v_mfma_f32_16x16x32_bf16 v[102:105], v[146:149], v[206:209], v[102:105]
	v_mfma_f32_16x16x32_bf16 v[102:105], v[150:153], v[228:231], v[102:105]
	v_mfma_f32_16x16x32_bf16 v[86:89], v[150:153], v[236:239], v[86:89]
	v_mfma_f32_16x16x32_bf16 v[86:89], v[146:149], v[232:235], v[86:89]
	v_mfma_f32_16x16x32_bf16 v[78:81], v[154:157], v[232:235], v[78:81]
	v_mfma_f32_16x16x32_bf16 v[78:81], v[158:161], v[236:239], v[78:81]
	v_mfma_f32_16x16x32_bf16 v[94:97], v[158:161], v[228:231], v[94:97]
	v_mfma_f32_16x16x32_bf16 v[94:97], v[154:157], v[206:209], v[94:97]
	v_mfma_f32_16x16x32_bf16 v[110:113], v[154:157], v[198:201], v[110:113]
	v_mfma_f32_16x16x32_bf16 v[110:113], v[158:161], v[202:205], v[110:113]
	v_mfma_f32_16x16x32_bf16 v[122:125], v[158:161], v[194:197], v[122:125]
	v_mfma_f32_16x16x32_bf16 v[122:125], v[154:157], v[190:193], v[122:125]
	v_mfma_f32_16x16x32_bf16 v[114:117], v[162:165], v[190:193], v[114:117]
	v_mfma_f32_16x16x32_bf16 v[114:117], v[166:169], v[194:197], v[114:117]
	v_mfma_f32_16x16x32_bf16 v[98:101], v[166:169], v[202:205], v[98:101]
	v_mfma_f32_16x16x32_bf16 v[98:101], v[162:165], v[198:201], v[98:101]
	v_mfma_f32_16x16x32_bf16 v[82:85], v[162:165], v[206:209], v[82:85]
	v_mfma_f32_16x16x32_bf16 v[82:85], v[166:169], v[228:231], v[82:85]
	v_mfma_f32_16x16x32_bf16 v[70:73], v[166:169], v[236:239], v[70:73]
	v_mfma_f32_16x16x32_bf16 v[70:73], v[162:165], v[232:235], v[70:73]
	v_mfma_f32_16x16x32_bf16 v[66:69], v[170:173], v[232:235], v[66:69]
	v_mfma_f32_16x16x32_bf16 v[66:69], v[178:181], v[236:239], v[66:69]
	v_mfma_f32_16x16x32_bf16 v[74:77], v[178:181], v[228:231], v[74:77]
	v_mfma_f32_16x16x32_bf16 v[74:77], v[170:173], v[206:209], v[74:77]
	v_mfma_f32_16x16x32_bf16 v[90:93], v[170:173], v[198:201], v[90:93]
	v_mfma_f32_16x16x32_bf16 v[90:93], v[178:181], v[202:205], v[90:93]
	v_mfma_f32_16x16x32_bf16 v[106:109], v[178:181], v[194:197], v[106:109]
	v_mfma_f32_16x16x32_bf16 v[106:109], v[170:173], v[190:193], v[106:109]
	s_barrier
	s_setprio 0
	s_add_i32 s14, s49, s26
	v_lshl_add_u64 v[140:141], v[140:141], 0, s[34:35]
	s_mov_b32 m0, s14
	s_nop 0
	global_load_lds_dwordx4 v[140:141], off
	ds_read_b128 v[190:193], v145 offset:49152
	ds_read_b128 v[194:197], v145 offset:50176
	s_add_i32 m0, s14, 0x2000
	s_add_u32 s14, s18, 0x2b0080
	v_lshl_add_u64 v[140:141], v[186:187], 0, s[34:35]
	s_addc_u32 s15, s19, 0
	s_add_i32 s18, s50, s26
	global_load_lds_dwordx4 v[140:141], off
	ds_read_b128 v[198:201], v145 offset:51200
	ds_read_b128 v[202:205], v145 offset:52224
	v_lshl_add_u64 v[140:141], s[14:15], 0, v[0:1]
	s_mov_b32 m0, s18
	s_nop 0
	global_load_lds_dwordx4 v[140:141], off
	ds_read_b128 v[206:209], v145 offset:53248
	ds_read_b128 v[228:231], v145 offset:54272
	v_lshl_add_u64 v[140:141], s[14:15], 0, v[130:131]
	s_add_i32 m0, s18, 0x2000
	s_nop 0
	global_load_lds_dwordx4 v[140:141], off
	ds_read_b128 v[232:235], v145 offset:55296
	ds_read_b128 v[236:239], v145 offset:56320
	v_lshl_add_u64 v[140:141], v[188:189], 0, s[34:35]
	s_mov_b32 m0, s39
	s_nop 0
	global_load_lds_dwordx4 v[140:141], off
	v_lshl_add_u64 v[140:141], v[210:211], 0, s[34:35]
	s_mov_b32 m0, s40
	s_nop 0
	global_load_lds_dwordx4 v[140:141], off
	s_waitcnt vmcnt(8)
	s_waitcnt lgkmcnt(0)
	s_setprio 1
	s_barrier
	v_mfma_f32_16x16x32_bf16 v[62:65], v[146:149], v[190:193], v[62:65]
	v_mfma_f32_16x16x32_bf16 v[62:65], v[150:153], v[194:197], v[62:65]
	v_mfma_f32_16x16x32_bf16 v[54:57], v[150:153], v[202:205], v[54:57]
	v_mfma_f32_16x16x32_bf16 v[54:57], v[146:149], v[198:201], v[54:57]
	v_mfma_f32_16x16x32_bf16 v[38:41], v[146:149], v[206:209], v[38:41]
	v_mfma_f32_16x16x32_bf16 v[38:41], v[150:153], v[228:231], v[38:41]
	v_mfma_f32_16x16x32_bf16 v[22:25], v[150:153], v[236:239], v[22:25]
	v_mfma_f32_16x16x32_bf16 v[22:25], v[146:149], v[232:235], v[22:25]
	v_mfma_f32_16x16x32_bf16 v[14:17], v[154:157], v[232:235], v[14:17]
	v_mfma_f32_16x16x32_bf16 v[14:17], v[158:161], v[236:239], v[14:17]
	v_mfma_f32_16x16x32_bf16 v[30:33], v[158:161], v[228:231], v[30:33]
	v_mfma_f32_16x16x32_bf16 v[30:33], v[154:157], v[206:209], v[30:33]
	v_mfma_f32_16x16x32_bf16 v[46:49], v[154:157], v[198:201], v[46:49]
	v_mfma_f32_16x16x32_bf16 v[46:49], v[158:161], v[202:205], v[46:49]
	v_mfma_f32_16x16x32_bf16 v[58:61], v[158:161], v[194:197], v[58:61]
	v_mfma_f32_16x16x32_bf16 v[58:61], v[154:157], v[190:193], v[58:61]
	v_mfma_f32_16x16x32_bf16 v[50:53], v[162:165], v[190:193], v[50:53]
	v_mfma_f32_16x16x32_bf16 v[50:53], v[166:169], v[194:197], v[50:53]
	v_mfma_f32_16x16x32_bf16 v[34:37], v[166:169], v[202:205], v[34:37]
	v_mfma_f32_16x16x32_bf16 v[34:37], v[162:165], v[198:201], v[34:37]
	v_mfma_f32_16x16x32_bf16 v[18:21], v[162:165], v[206:209], v[18:21]
	v_mfma_f32_16x16x32_bf16 v[18:21], v[166:169], v[228:231], v[18:21]
	v_mfma_f32_16x16x32_bf16 v[6:9], v[166:169], v[236:239], v[6:9]
	v_mfma_f32_16x16x32_bf16 v[6:9], v[162:165], v[232:235], v[6:9]
	v_mfma_f32_16x16x32_bf16 v[2:5], v[170:173], v[232:235], v[2:5]
	v_mfma_f32_16x16x32_bf16 v[2:5], v[178:181], v[236:239], v[2:5]
	v_mfma_f32_16x16x32_bf16 v[10:13], v[178:181], v[228:231], v[10:13]
	v_mfma_f32_16x16x32_bf16 v[10:13], v[170:173], v[206:209], v[10:13]
	v_mfma_f32_16x16x32_bf16 v[26:29], v[170:173], v[198:201], v[26:29]
	v_mfma_f32_16x16x32_bf16 v[26:29], v[178:181], v[202:205], v[26:29]
	v_mfma_f32_16x16x32_bf16 v[42:45], v[178:181], v[194:197], v[42:45]
	v_mfma_f32_16x16x32_bf16 v[42:45], v[170:173], v[190:193], v[42:45]
	s_barrier
	s_setprio 0
	s_add_i32 s48, s48, 2
	s_add_u32 s46, s46, 0x100
	s_addc_u32 s47, s47, 0
	s_cmpk_gt_u32 s48, 0xa9
	s_mov_b64 s[14:15], s[16:17]
	s_cbranch_scc0 .LBB0_805
	s_and_b64 vcc, exec, s[6:7]
	s_cbranch_vccz .LBB0_808
	s_barrier
